# tile-start de-serialisation: accumulator clear with v_mov_b64 pairs (64 instead of 127 moves per tile) in four GEMM phases
# speedup vs baseline: 1.0051x; 1.0001x over previous
; template <class Epi, class Sched, bool ALIGN_EPI = false, bool SP2 = false>
; __device__ __forceinline__ void gemm_phase(PG8_LAS unsigned char* lds, const Gemm g, const Sched& S, const Epi& E) {
;     ...
;         for (int a = 0; a < 2; ++a)
; #pragma unroll
;             for (int b = 0; b < 2; ++b)
; #pragma unroll
;                 for (int m = 0; m < 4; ++m)
; #pragma unroll
;                     for (int n = 0; n < 2; ++n) acc[a][b][m][n] = (f32x4){0.f, 0.f, 0.f, 0.f};
;         }
;         cur = nxt; cA = nA; cB = nB; ++ui;
.LBB0_164:
	s_ashr_i32 s25, s24, 31
	s_lshl_b64 s[36:37], s[24:25], 20
	s_add_u32 s36, s56, s36
	s_addc_u32 s37, s57, s37
	s_and_b64 s[40:41], s[38:39], exec
	s_cselect_b32 s17, s37, s27
	s_cselect_b32 s25, s36, s26
	s_ashr_i32 s23, s22, 31
	s_lshl_b64 s[40:41], s[22:23], 20
	s_add_u32 s42, s47, s40
	s_addc_u32 s43, s48, s41
	s_and_b64 s[40:41], s[38:39], exec
	s_cselect_b32 s23, s43, s29
	s_cselect_b32 s54, s42, s28
	s_add_u32 s26, s26, 0x80080
	s_addc_u32 s27, s27, 0
	s_add_u32 s55, s28, 0x100
	v_mov_b32_e32 v2, 0
	s_addc_u32 s73, s29, 0
	s_mov_b32 s77, -2
	v_mov_b32_e32 v3, v2
	v_mov_b32_e32 v4, v2
	v_mov_b32_e32 v5, v2
	v_mov_b32_e32 v10, v2
	v_mov_b32_e32 v11, v2
	v_mov_b32_e32 v12, v2
	v_mov_b32_e32 v13, v2
	s_waitcnt lgkmcnt(0)
	v_mov_b64_e32 v[6:7], 0
	v_mov_b64_e32 v[8:9], 0
	v_mov_b64_e32 v[14:15], 0
	v_mov_b64_e32 v[16:17], 0
	v_mov_b64_e32 v[18:19], 0
	v_mov_b64_e32 v[20:21], 0
	v_mov_b64_e32 v[22:23], 0
	v_mov_b64_e32 v[24:25], 0
	v_mov_b64_e32 v[26:27], 0
	v_mov_b64_e32 v[28:29], 0
	v_mov_b64_e32 v[30:31], 0
	v_mov_b64_e32 v[32:33], 0
	v_mov_b64_e32 v[34:35], 0
	v_mov_b64_e32 v[36:37], 0
	v_mov_b64_e32 v[38:39], 0
	v_mov_b64_e32 v[40:41], 0
	v_mov_b64_e32 v[42:43], 0
	v_mov_b64_e32 v[44:45], 0
	v_mov_b64_e32 v[46:47], 0
	v_mov_b64_e32 v[48:49], 0
	v_mov_b64_e32 v[50:51], 0
	v_mov_b64_e32 v[52:53], 0
	v_mov_b64_e32 v[54:55], 0
	v_mov_b64_e32 v[56:57], 0
	v_mov_b64_e32 v[58:59], 0
	v_mov_b64_e32 v[60:61], 0
	v_mov_b64_e32 v[62:63], 0
	v_mov_b64_e32 v[64:65], 0
	v_mov_b64_e32 v[66:67], 0
	v_mov_b64_e32 v[68:69], 0
	v_mov_b64_e32 v[70:71], 0
	v_mov_b64_e32 v[72:73], 0
	v_mov_b64_e32 v[74:75], 0
	v_mov_b64_e32 v[76:77], 0
	v_mov_b64_e32 v[78:79], 0
	v_mov_b64_e32 v[80:81], 0
	v_mov_b64_e32 v[82:83], 0
	v_mov_b64_e32 v[84:85], 0
	v_mov_b64_e32 v[86:87], 0
	v_mov_b64_e32 v[88:89], 0
	v_mov_b64_e32 v[90:91], 0
	v_mov_b64_e32 v[92:93], 0
	v_mov_b64_e32 v[94:95], 0
	v_mov_b64_e32 v[96:97], 0
	v_mov_b64_e32 v[98:99], 0
	v_mov_b64_e32 v[100:101], 0
	v_mov_b64_e32 v[102:103], 0
	v_mov_b64_e32 v[104:105], 0
	v_mov_b64_e32 v[106:107], 0
	v_mov_b64_e32 v[108:109], 0
	v_mov_b64_e32 v[110:111], 0
	v_mov_b64_e32 v[112:113], 0
	v_mov_b64_e32 v[114:115], 0
	v_mov_b64_e32 v[116:117], 0
	v_mov_b64_e32 v[118:119], 0
	v_mov_b64_e32 v[120:121], 0
	v_mov_b64_e32 v[122:123], 0
	v_mov_b64_e32 v[124:125], 0
	v_mov_b64_e32 v[126:127], 0
	v_mov_b64_e32 v[128:129], 0

; template <class Epi, class Sched, bool ALIGN_EPI = false, bool SP2 = false>
; __device__ __forceinline__ void gemm_phase(PG8_LAS unsigned char* lds, const Gemm g, const Sched& S, const Epi& E) {
;     ...
;         for (int a = 0; a < 2; ++a)
; #pragma unroll
;             for (int b = 0; b < 2; ++b)
; #pragma unroll
;                 for (int m = 0; m < 4; ++m)
; #pragma unroll
;                     for (int n = 0; n < 2; ++n) acc[a][b][m][n] = (f32x4){0.f, 0.f, 0.f, 0.f};
;         }
;         cur = nxt; cA = nA; cB = nB; ++ui;
.LBB0_552:
	s_ashr_i32 s23, s22, 31
	s_lshl_b64 s[24:25], s[22:23], 20
	s_add_u32 s24, s14, s24
	s_addc_u32 s25, s15, s25
	s_and_b64 s[28:29], s[44:45], exec
	s_cselect_b32 s23, s25, s17
	s_cselect_b32 s38, s24, s16
	s_ashr_i32 s21, s20, 31
	s_lshl_b64 s[28:29], s[20:21], 20
	s_add_u32 s36, s46, s28
	s_addc_u32 s37, s47, s29
	s_and_b64 s[28:29], s[44:45], exec
	s_cselect_b32 s21, s37, s27
	s_cselect_b32 s39, s36, s26
	s_add_u32 s16, s16, 0x80080
	s_addc_u32 s17, s17, 0
	s_add_u32 s78, s26, 0x100
	v_mov_b32_e32 v2, 0
	s_addc_u32 vcc_lo, s27, 0
	s_mov_b32 vcc_hi, -2
	s_waitcnt lgkmcnt(0)
	v_mov_b64_e32 v[2:3], 0
	v_mov_b64_e32 v[4:5], 0
	v_mov_b64_e32 v[6:7], 0
	v_mov_b64_e32 v[8:9], 0
	v_mov_b64_e32 v[10:11], 0
	v_mov_b64_e32 v[12:13], 0
	v_mov_b64_e32 v[14:15], 0
	v_mov_b64_e32 v[16:17], 0
	v_mov_b64_e32 v[18:19], 0
	v_mov_b64_e32 v[20:21], 0
	v_mov_b64_e32 v[22:23], 0
	v_mov_b64_e32 v[24:25], 0
	v_mov_b64_e32 v[26:27], 0
	v_mov_b64_e32 v[28:29], 0
	v_mov_b64_e32 v[30:31], 0
	v_mov_b64_e32 v[32:33], 0
	v_mov_b64_e32 v[34:35], 0
	v_mov_b64_e32 v[36:37], 0
	v_mov_b64_e32 v[38:39], 0
	v_mov_b64_e32 v[40:41], 0
	v_mov_b64_e32 v[42:43], 0
	v_mov_b64_e32 v[44:45], 0
	v_mov_b64_e32 v[46:47], 0
	v_mov_b64_e32 v[48:49], 0
	v_mov_b64_e32 v[50:51], 0
	v_mov_b64_e32 v[52:53], 0
	v_mov_b64_e32 v[54:55], 0
	v_mov_b64_e32 v[56:57], 0
	v_mov_b64_e32 v[58:59], 0
	v_mov_b64_e32 v[60:61], 0
	v_mov_b64_e32 v[62:63], 0
	v_mov_b64_e32 v[64:65], 0
	v_mov_b64_e32 v[66:67], 0
	v_mov_b64_e32 v[68:69], 0
	v_mov_b64_e32 v[70:71], 0
	v_mov_b64_e32 v[72:73], 0
	v_mov_b64_e32 v[74:75], 0
	v_mov_b64_e32 v[76:77], 0
	v_mov_b64_e32 v[78:79], 0
	v_mov_b64_e32 v[80:81], 0
	v_mov_b64_e32 v[82:83], 0
	v_mov_b64_e32 v[84:85], 0
	v_mov_b64_e32 v[86:87], 0
	v_mov_b64_e32 v[88:89], 0
	v_mov_b64_e32 v[90:91], 0
	v_mov_b64_e32 v[92:93], 0
	v_mov_b64_e32 v[94:95], 0
	v_mov_b64_e32 v[96:97], 0
	v_mov_b64_e32 v[98:99], 0
	v_mov_b64_e32 v[100:101], 0
	v_mov_b64_e32 v[102:103], 0
	v_mov_b64_e32 v[104:105], 0
	v_mov_b64_e32 v[106:107], 0
	v_mov_b64_e32 v[108:109], 0
	v_mov_b64_e32 v[110:111], 0
	v_mov_b64_e32 v[112:113], 0
	v_mov_b64_e32 v[126:127], 0
	v_mov_b64_e32 v[128:129], 0
	v_mov_b64_e32 v[130:131], 0
	v_mov_b64_e32 v[132:133], 0
	v_mov_b64_e32 v[138:139], 0
	v_mov_b64_e32 v[140:141], 0
	v_mov_b64_e32 v[142:143], 0
	v_mov_b64_e32 v[144:145], 0

; template <class Epi, class Sched, bool ALIGN_EPI = false, bool SP2 = false>
; __device__ __forceinline__ void gemm_phase(PG8_LAS unsigned char* lds, const Gemm g, const Sched& S, const Epi& E) {
;     ...
;         for (int a = 0; a < 2; ++a)
; #pragma unroll
;             for (int b = 0; b < 2; ++b)
; #pragma unroll
;                 for (int m = 0; m < 4; ++m)
; #pragma unroll
;                     for (int n = 0; n < 2; ++n) acc[a][b][m][n] = (f32x4){0.f, 0.f, 0.f, 0.f};
;         }
;         cur = nxt; cA = nA; cB = nB; ++ui;
.LBB0_658:
	s_ashr_i32 s23, s22, 31
	s_lshl_b64 s[24:25], s[22:23], 20
	s_add_u32 s24, s56, s24
	s_addc_u32 s25, s57, s25
	s_and_b64 s[28:29], s[40:41], exec
	s_cselect_b32 s23, s25, s17
	s_cselect_b32 s43, s24, s16
	s_ashr_i32 s21, s20, 31
	s_lshl_b64 s[28:29], s[20:21], 20
	s_add_u32 s36, s39, s28
	s_addc_u32 s37, s44, s29
	s_and_b64 s[28:29], s[40:41], exec
	s_cselect_b32 s21, s37, s27
	s_cselect_b32 s52, s36, s26
	s_add_u32 s16, s16, 0x80080
	s_addc_u32 s17, s17, 0
	s_add_u32 s53, s26, 0x100
	v_mov_b32_e32 v2, 0
	s_addc_u32 s73, s27, 0
	s_mov_b32 s77, -2
	v_mov_b64_e32 v[2:3], 0
	v_mov_b64_e32 v[4:5], 0
	v_mov_b64_e32 v[6:7], 0
	v_mov_b64_e32 v[8:9], 0
	v_mov_b64_e32 v[10:11], 0
	v_mov_b64_e32 v[12:13], 0
	v_mov_b64_e32 v[14:15], 0
	v_mov_b64_e32 v[16:17], 0
	v_mov_b64_e32 v[18:19], 0
	v_mov_b64_e32 v[20:21], 0
	v_mov_b64_e32 v[22:23], 0
	v_mov_b64_e32 v[24:25], 0
	v_mov_b64_e32 v[26:27], 0
	v_mov_b64_e32 v[28:29], 0
	v_mov_b64_e32 v[30:31], 0
	v_mov_b64_e32 v[32:33], 0
	v_mov_b64_e32 v[34:35], 0
	v_mov_b64_e32 v[36:37], 0
	v_mov_b64_e32 v[38:39], 0
	v_mov_b64_e32 v[40:41], 0
	v_mov_b64_e32 v[42:43], 0
	v_mov_b64_e32 v[44:45], 0
	v_mov_b64_e32 v[46:47], 0
	v_mov_b64_e32 v[48:49], 0
	v_mov_b64_e32 v[50:51], 0
	v_mov_b64_e32 v[52:53], 0
	v_mov_b64_e32 v[54:55], 0
	v_mov_b64_e32 v[56:57], 0
	v_mov_b64_e32 v[58:59], 0
	v_mov_b64_e32 v[60:61], 0
	v_mov_b64_e32 v[62:63], 0
	v_mov_b64_e32 v[64:65], 0
	v_mov_b64_e32 v[66:67], 0
	v_mov_b64_e32 v[68:69], 0
	v_mov_b64_e32 v[70:71], 0
	v_mov_b64_e32 v[72:73], 0
	v_mov_b64_e32 v[74:75], 0
	v_mov_b64_e32 v[76:77], 0
	v_mov_b64_e32 v[78:79], 0
	v_mov_b64_e32 v[80:81], 0
	v_mov_b64_e32 v[82:83], 0
	v_mov_b64_e32 v[84:85], 0
	v_mov_b64_e32 v[86:87], 0
	v_mov_b64_e32 v[88:89], 0
	v_mov_b64_e32 v[90:91], 0
	v_mov_b64_e32 v[92:93], 0
	v_mov_b64_e32 v[94:95], 0
	v_mov_b64_e32 v[96:97], 0
	v_mov_b64_e32 v[98:99], 0
	v_mov_b64_e32 v[100:101], 0
	v_mov_b64_e32 v[102:103], 0
	v_mov_b64_e32 v[104:105], 0
	v_mov_b64_e32 v[106:107], 0
	v_mov_b64_e32 v[108:109], 0
	v_mov_b64_e32 v[110:111], 0
	v_mov_b64_e32 v[112:113], 0
	v_mov_b64_e32 v[114:115], 0
	v_mov_b64_e32 v[116:117], 0
	v_mov_b64_e32 v[118:119], 0
	v_mov_b64_e32 v[120:121], 0
	v_mov_b64_e32 v[122:123], 0
	v_mov_b64_e32 v[124:125], 0
	v_mov_b64_e32 v[126:127], 0
	v_mov_b64_e32 v[128:129], 0

; template <class Epi, class Sched, bool ALIGN_EPI = false, bool SP2 = false>
; __device__ __forceinline__ void gemm_phase(PG8_LAS unsigned char* lds, const Gemm g, const Sched& S, const Epi& E) {
;     ...
;         for (int a = 0; a < 2; ++a)
; #pragma unroll
;             for (int b = 0; b < 2; ++b)
; #pragma unroll
;                 for (int m = 0; m < 4; ++m)
; #pragma unroll
;                     for (int n = 0; n < 2; ++n) acc[a][b][m][n] = (f32x4){0.f, 0.f, 0.f, 0.f};
;         }
;         cur = nxt; cA = nA; cB = nB; ++ui;
.LBB0_801:
	s_add_u32 s44, s24, 0x100
	v_mov_b32_e32 v2, 0
	s_addc_u32 s45, s25, 0
	s_mov_b32 s78, -2
	s_waitcnt lgkmcnt(0)
	v_mov_b64_e32 v[2:3], 0
	v_mov_b64_e32 v[4:5], 0
	v_mov_b64_e32 v[6:7], 0
	v_mov_b64_e32 v[8:9], 0
	v_mov_b64_e32 v[10:11], 0
	v_mov_b64_e32 v[12:13], 0
	v_mov_b64_e32 v[14:15], 0
	v_mov_b64_e32 v[16:17], 0
	v_mov_b64_e32 v[18:19], 0
	v_mov_b64_e32 v[20:21], 0
	v_mov_b64_e32 v[22:23], 0
	v_mov_b64_e32 v[24:25], 0
	v_mov_b64_e32 v[26:27], 0
	v_mov_b64_e32 v[28:29], 0
	v_mov_b64_e32 v[30:31], 0
	v_mov_b64_e32 v[32:33], 0
	v_mov_b64_e32 v[34:35], 0
	v_mov_b64_e32 v[36:37], 0
	v_mov_b64_e32 v[38:39], 0
	v_mov_b64_e32 v[40:41], 0
	v_mov_b64_e32 v[42:43], 0
	v_mov_b64_e32 v[44:45], 0
	v_mov_b64_e32 v[46:47], 0
	v_mov_b64_e32 v[48:49], 0
	v_mov_b64_e32 v[50:51], 0
	v_mov_b64_e32 v[52:53], 0
	v_mov_b64_e32 v[54:55], 0
	v_mov_b64_e32 v[56:57], 0
	v_mov_b64_e32 v[58:59], 0
	v_mov_b64_e32 v[60:61], 0
	v_mov_b64_e32 v[62:63], 0
	v_mov_b64_e32 v[64:65], 0
	v_mov_b64_e32 v[66:67], 0
	v_mov_b64_e32 v[68:69], 0
	v_mov_b64_e32 v[70:71], 0
	v_mov_b64_e32 v[72:73], 0
	v_mov_b64_e32 v[74:75], 0
	v_mov_b64_e32 v[76:77], 0
	v_mov_b64_e32 v[78:79], 0
	v_mov_b64_e32 v[80:81], 0
	v_mov_b64_e32 v[82:83], 0
	v_mov_b64_e32 v[84:85], 0
	v_mov_b64_e32 v[86:87], 0
	v_mov_b64_e32 v[88:89], 0
	v_mov_b64_e32 v[90:91], 0
	v_mov_b64_e32 v[92:93], 0
	v_mov_b64_e32 v[94:95], 0
	v_mov_b64_e32 v[96:97], 0
	v_mov_b64_e32 v[98:99], 0
	v_mov_b64_e32 v[100:101], 0
	v_mov_b64_e32 v[102:103], 0
	v_mov_b64_e32 v[104:105], 0
	v_mov_b64_e32 v[106:107], 0
	v_mov_b64_e32 v[108:109], 0
	v_mov_b64_e32 v[110:111], 0
	v_mov_b64_e32 v[112:113], 0
	v_mov_b64_e32 v[114:115], 0
	v_mov_b64_e32 v[116:117], 0
	v_mov_b64_e32 v[118:119], 0
	v_mov_b64_e32 v[120:121], 0
	v_mov_b64_e32 v[126:127], 0
	v_mov_b64_e32 v[128:129], 0
	v_mov_b64_e32 v[130:131], 0
	v_mov_b64_e32 v[132:133], 0
